# attention tile loop instruction selection: clamp folded into one v_min (16 fewer VALU per 32-key block), K/V staging addresses from one 64-bit mad plus adds and a negative load offset
# baseline (speedup 1.0000x reference)
; #define GROUP_LOOP(qi, total, ...) for (int gi_ = 0;; ++gi_) { if (threadIdx.x == 0) ctlw[22 + (gi_ & 1)] = __hip_atomic_fetch_add(qbase + 64 * (qi), 1u, __ATOMIC_RELAXED, __HIP_MEMORY_SCOPE_AGENT); \
;         group_bar(gb, lane); const int u = (int)ctlw[22 + (gi_ & 1)]; if (u >= (total)) break; __VA_ARGS__ }
; template <int MASK> __device__ __forceinline__ void phase3(const Params& p, LAS unsigned char* lds, volatile LAS unsigned* ctlw, int qset) {
;     ...
;     const unsigned gb0 = __builtin_amdgcn_readfirstlane(ctlw[20]);
;     __syncthreads();
;     {
;         int tid = threadIdx.x; asm volatile("" : "+v"(tid));
;         const int wid = __builtin_amdgcn_readfirstlane(tid >> 6), lane = tid & 63;
;         if (wid < 4) {
;             GroupBar gb; gb.cnt = ctlw + 20; gb.gen = gb0;
;             __builtin_amdgcn_s_setprio(1);
;             GROUP_LOOP(2, U_SB, {
.LBB0_835:
	s_add_i32 s53, 0, 0x27e50
	v_mov_b32_e32 v1, s53
	ds_read_b32 v1, v1
	v_mov_b32_e32 v193, v0
	s_waitcnt lgkmcnt(0)
	s_barrier
	s_mov_b32 s45, 0
	v_readfirstlane_b32 s2, v193
	s_ashr_i32 s24, s2, 6
	v_and_b32_e32 v169, 63, v193
	v_readfirstlane_b32 s54, v1
	s_cmp_gt_i32 s24, 3
	v_cmp_eq_u32_e64 s[2:3], 0, v169
	s_cbranch_scc1 .LBB0_961
	s_add_u32 s33, s90, 0xe000000
	s_addc_u32 s52, s91, 0
	s_setprio 1
	s_mov_b32 s99, 0x42c80000
	s_mov_b32 s100, 0x36000
	s_mov_b32 s101, 0
	v_mov_b32_e32 v3, 0
	v_mov_b32_e32 v194, s53
	s_movk_i32 s55, 0x3600
	s_movk_i32 s62, 0x70
	s_mov_b32 s63, 0xfffff0
	s_movk_i32 s64, 0xc0
	s_movk_i32 s65, 0x60
	s_movk_i32 s66, 0x80
	s_movk_i32 s67, 0xa0
	s_movk_i32 s70, 0xe0
	s_movk_i32 s71, 0x118
	s_mov_b32 s72, 0
	s_branch .LBB0_839

; #define SLOAD(k0) do { _Pragma("unroll") for (int j_ = 0; j_ < 4; ++j_) { sv[j_] = *(const bf16x8*)(a.V + (size_t)((k0) + sr + 16 * j_) * a.kvstride + sc); \
;         sk[j_] = *(const bf16x8*)(a.K + (size_t)((k0) + sr + 16 * j_) * a.kvstride + sc); } } while (0)
; template <int MODE> ...
;     ...
;     for (int j = 0; j < nt; ++j) {
;         const int cur = j & 1, t = (MODE == 0) ? nt - 1 - j : j;
;         if (j + 1 < nt) { const int tn = (MODE == 0) ? t - 1 : t + 1; SLOAD(tn * 64); }
.LBB0_860:
	s_sub_i32 s9, s82, s8
	s_add_i32 s85, s8, 1
	s_cmp_lt_u32 s85, s83
	s_cselect_b64 s[46:47], -1, 0
	s_lshl_b32 s10, s9, 6
	s_cmp_ge_u32 s85, s83
	s_cbranch_scc1 .LBB0_871
	v_add_u32_e32 v2, s10, v209
	v_mad_i64_i32 v[84:85], s[12:13], v2, s55, v[166:167]
	global_load_dwordx4 v[132:135], v[84:85], off
	global_load_dwordx4 v[136:139], v[84:85], off offset:-2048
	v_lshl_add_u64 v[86:87], v[84:85], 0, s[100:101]
	global_load_dwordx4 v[140:143], v[86:87], off
	global_load_dwordx4 v[144:147], v[86:87], off offset:-2048
	v_lshl_add_u64 v[84:85], v[86:87], 0, s[100:101]
	global_load_dwordx4 v[148:151], v[84:85], off
	global_load_dwordx4 v[152:155], v[84:85], off offset:-2048
	v_lshl_add_u64 v[86:87], v[84:85], 0, s[100:101]
	global_load_dwordx4 v[156:159], v[86:87], off
	global_load_dwordx4 v[160:163], v[86:87], off offset:-2048
	s_and_b32 s86, s8, 1
	s_cmp_ge_i32 s10, s84
	s_cbranch_scc0 .LBB0_872

; __device__ __forceinline__ float fast_exp2(float x) { return __builtin_amdgcn_exp2f(x); }
; __device__ __forceinline__ float fast_rcp(float x) { return __builtin_amdgcn_rcpf(x); }
; template <int NB, bool MASK> __device__ __forceinline__ void sb_transform(f32x16* P, float& R, int hi, int kpos0, int qpos) {
;     float T[NB][4];
; #pragma unroll
;     for (int b = 0; b < NB; ++b)
; #pragma unroll
;         for (int g = 0; g < 4; ++g) {
;             float be[4], f[4];
; #pragma unroll
;             for (int i = 0; i < 4; ++i) {
;                 const float z = fmaxf(P[b][4 * g + i], -100.f);
;                 const float e = fast_exp2(-z), rc = fast_rcp(1.f + e);
;                 be[i] = rc; f[i] = e * rc;
;                 if (MASK) { const bool ok = (kpos0 + 32 * b + 8 * g + 4 * hi + i) < qpos; be[i] = ok ? be[i] : 0.f; f[i] = ok ? f[i] : 1.f; }
;             }
.LBB0_872:
	s_lshl_b32 s87, s86, 14
	v_add_u32_e32 v2, s87, v211
	v_add_u32_e32 v172, v2, v212
	ds_read_b128 v[176:179], v172 offset:40960
	v_add_u32_e32 v174, v2, v213
	ds_read_b128 v[180:183], v174 offset:40960
	v_add_u32_e32 v175, v2, v214
	s_or_b32 s11, s10, 63
	s_cmp_ge_i32 s11, s78
	s_mov_b64 s[8:9], -1
	s_cselect_b64 s[50:51], -1, 0
	s_cmp_lt_i32 s11, s78
	s_waitcnt lgkmcnt(1)
	v_mfma_f32_32x32x16_bf16 v[84:99], v[176:179], v[100:103], v[68:83]
	v_add_u32_e32 v176, v2, v215
	v_add_u32_e32 v177, v2, v216
	s_waitcnt lgkmcnt(0)
	v_mfma_f32_32x32x16_bf16 v[84:99], v[180:183], v[104:107], v[84:99]
	ds_read_b128 v[178:181], v175 offset:40960
	ds_read_b128 v[182:185], v176 offset:40960
	s_waitcnt lgkmcnt(1)
	v_mfma_f32_32x32x16_bf16 v[84:99], v[178:181], v[108:111], v[84:99]
	v_add_u32_e32 v178, v2, v217
	v_add_u32_e32 v179, v2, v218
	s_waitcnt lgkmcnt(0)
	v_mfma_f32_32x32x16_bf16 v[84:99], v[182:185], v[112:115], v[84:99]
	ds_read_b128 v[180:183], v177 offset:40960
	ds_read_b128 v[184:187], v178 offset:40960
	s_waitcnt lgkmcnt(1)
	v_mfma_f32_32x32x16_bf16 v[84:99], v[180:183], v[116:119], v[84:99]
	v_add_u32_e32 v180, v2, v219
	v_or_b32_e32 v2, s10, v210
	s_waitcnt lgkmcnt(0)
	v_mfma_f32_32x32x16_bf16 v[84:99], v[184:187], v[120:123], v[84:99]
	ds_read_b128 v[182:185], v179 offset:40960
	ds_read_b128 v[186:189], v180 offset:40960
	s_waitcnt lgkmcnt(1)
	v_mfma_f32_32x32x16_bf16 v[84:99], v[182:185], v[124:127], v[84:99]
	s_waitcnt lgkmcnt(0)
	v_mfma_f32_32x32x16_bf16 v[84:99], v[186:189], v[128:131], v[84:99]
	s_nop 11
	v_min_f32_e64 v227, -v84, s99
	v_min_f32_e64 v226, -v85, s99
	v_min_f32_e64 v225, -v86, s99
	v_min_f32_e64 v224, -v87, s99
	v_min_f32_e64 v223, -v88, s99
	v_min_f32_e64 v222, -v89, s99
	v_min_f32_e64 v221, -v90, s99
	v_min_f32_e64 v189, -v91, s99
	v_min_f32_e64 v188, -v92, s99
	v_min_f32_e64 v187, -v93, s99
	v_min_f32_e64 v186, -v94, s99
	v_min_f32_e64 v185, -v95, s99
	v_min_f32_e64 v183, -v96, s99
	v_min_f32_e64 v184, -v97, s99
	v_min_f32_e64 v182, -v98, s99
	v_min_f32_e64 v181, -v99, s99
	s_cbranch_scc1 .LBB0_874
	v_exp_f32_e32 v84, v227
	v_exp_f32_e32 v85, v226
	v_or_b32_e32 v87, 32, v2
	v_add_f32_e32 v86, 1.0, v84
	v_rcp_f32_e32 v86, v86
	v_add_f32_e32 v88, 1.0, v85
	v_rcp_f32_e32 v88, v88
	v_mul_f32_e32 v89, v84, v86
	v_cmp_lt_i32_e32 vcc, v87, v168
	v_exp_f32_e32 v90, v224
	v_mul_f32_e32 v87, v85, v88
	v_cndmask_b32_e32 v84, 0, v86, vcc
	v_cndmask_b32_e32 v86, 1.0, v89, vcc
	v_or_b32_e32 v89, 33, v2
	v_mov_b32_e32 v85, s45
	v_cmp_lt_i32_e32 vcc, v89, v168
	v_exp_f32_e32 v93, v223
	v_cndmask_b32_e32 v85, v85, v88, vcc
	v_exp_f32_e32 v92, v225
	v_add_f32_e32 v88, 1.0, v90
	v_rcp_f32_e32 v89, v88
	v_exp_f32_e32 v91, v222
	v_cndmask_b32_e32 v88, 1.0, v87, vcc
	v_add_f32_e32 v87, 1.0, v92
	v_rcp_f32_e32 v96, v87
	v_mul_f32_e32 v87, v90, v89
	v_or_b32_e32 v90, 35, v2
	v_cmp_lt_i32_e32 vcc, v90, v168
	v_add_f32_e32 v90, 1.0, v91
	v_rcp_f32_e32 v95, v90
	v_exp_f32_e32 v90, v221
	v_cndmask_b32_e32 v94, 1.0, v87, vcc
	v_add_f32_e32 v87, 1.0, v93
	v_rcp_f32_e32 v97, v87
	v_add_f32_e32 v98, 1.0, v90
	v_rcp_f32_e32 v99, v98
	v_exp_f32_e32 v98, v189
	v_mul_f32_e32 v87, v91, v95
	v_or_b32_e32 v91, 41, v2
	v_cmp_lt_i32_e64 s[8:9], v91, v168
	v_exp_f32_e32 v91, v188
	v_cndmask_b32_e64 v173, 1.0, v87, s[8:9]
	v_mul_f32_e32 v87, v90, v99
	v_add_f32_e32 v90, 1.0, v98
	v_rcp_f32_e32 v231, v90
	v_or_b32_e32 v90, 42, v2
	v_cmp_lt_i32_e64 s[10:11], v90, v168
	v_or_b32_e32 v90, 43, v2
	v_cmp_lt_i32_e64 s[12:13], v90, v168
	v_cndmask_b32_e64 v248, 1.0, v87, s[10:11]
	v_mul_f32_e32 v87, v98, v231
	v_cndmask_b32_e64 v249, 1.0, v87, s[12:13]
	v_add_f32_e32 v90, 1.0, v91
	v_exp_f32_e32 v87, v187
	v_rcp_f32_e32 v242, v90
	v_or_b32_e32 v90, 48, v2
	v_cmp_lt_i32_e64 s[14:15], v90, v168
	v_add_f32_e32 v98, 1.0, v87
	v_mul_f32_e32 v91, v91, v242
	v_rcp_f32_e32 v243, v98
	v_cndmask_b32_e64 v98, 1.0, v91, s[14:15]
	v_exp_f32_e32 v91, v185
	v_exp_f32_e32 v232, v184
	v_or_b32_e32 v229, 51, v2
	v_exp_f32_e32 v90, v186
	v_add_f32_e32 v228, 1.0, v91
	v_cmp_lt_i32_e64 s[20:21], v229, v168
	v_add_f32_e32 v229, 1.0, v232
	v_rcp_f32_e32 v244, v228
	v_rcp_f32_e32 v245, v229
	v_or_b32_e32 v170, 49, v2
	v_exp_f32_e32 v233, v182
	v_mul_f32_e32 v87, v87, v243
	v_cmp_lt_i32_e64 s[16:17], v170, v168
	v_pk_mul_f32 v[92:93], v[92:93], v[96:97]
	v_add_f32_e32 v234, 1.0, v233
	v_cndmask_b32_e64 v170, 1.0, v87, s[16:17]
	v_add_f32_e32 v87, 1.0, v90
	v_rcp_f32_e32 v228, v87
	v_mul_f32_e32 v87, v91, v244
	v_exp_f32_e32 v91, v183
	v_rcp_f32_e32 v246, v234
	v_exp_f32_e32 v234, v181
	v_cndmask_b32_e64 v230, 1.0, v87, s[20:21]
	v_add_f32_e32 v87, 1.0, v91
	v_rcp_f32_e32 v229, v87
	v_mul_f32_e32 v87, v232, v245
	v_or_b32_e32 v232, 57, v2
	v_cmp_lt_i32_e64 s[26:27], v232, v168
	v_add_f32_e32 v232, 1.0, v234
	v_rcp_f32_e32 v250, v232
	v_or_b32_e32 v232, 58, v2
	v_cndmask_b32_e64 v247, 1.0, v87, s[26:27]
	v_mul_f32_e32 v87, v233, v246
	v_cmp_lt_i32_e64 s[22:23], v232, v168
	v_or_b32_e32 v232, 59, v2
	v_cmp_lt_i32_e64 s[18:19], v232, v168
	v_cndmask_b32_e64 v251, 1.0, v87, s[22:23]
	v_mul_f32_e32 v87, v234, v250
	v_cndmask_b32_e64 v252, 1.0, v87, s[18:19]
	v_xor_b32_e32 v87, 32, v191
	v_add_u32_e32 v232, 64, v192
	v_cmp_lt_i32_e64 s[28:29], v87, v232
	v_or_b32_e32 v232, 50, v2
	v_pk_mul_f32 v[90:91], v[90:91], v[228:229]
	v_cndmask_b32_e64 v87, v191, v87, s[28:29]
	v_lshlrev_b32_e32 v253, 2, v87
	v_or_b32_e32 v87, 56, v2
	v_cmp_lt_i32_e64 s[28:29], v87, v1
	v_or_b32_e32 v87, 34, v2
	v_cmp_lt_i32_e64 s[30:31], v232, v168
	v_cmp_lt_i32_e64 s[34:35], v87, v168
	v_cndmask_b32_e64 v233, 1.0, v91, s[28:29]
	v_cndmask_b32_e64 v232, 1.0, v90, s[30:31]
	v_cndmask_b32_e64 v90, 0, v96, s[34:35]
	v_or_b32_e32 v91, 40, v2
	v_mov_b32_e32 v87, s45
	v_mul_f32_e32 v234, v94, v90
	v_mov_b32_e32 v90, s45
	v_cndmask_b32_e32 v235, v87, v89, vcc
	v_cmp_lt_i32_e32 vcc, v91, v1
	v_cndmask_b32_e64 v90, v90, v99, s[10:11]
	v_mul_f32_e32 v91, v251, v252
	v_cndmask_b32_e64 v241, v87, v231, s[12:13]
	v_mul_f32_e32 v240, v249, v90
	v_mov_b32_e32 v90, s45
	v_mul_f32_e32 v231, v247, v91
	v_cndmask_b32_e64 v236, 1.0, v92, s[34:35]
	v_cndmask_b32_e64 v96, v90, v242, s[14:15]
	v_cndmask_b32_e64 v90, 0, v228, s[30:31]
	v_cndmask_b32_e64 v92, 0, v229, s[28:29]
	v_pk_mul_f32 v[228:229], v[232:233], v[230:231]
	v_mov_b32_e32 v99, v229
	v_mov_b32_e32 v255, v229
	s_nop 1
	v_permlane32_swap_b32_e32 v99, v255
	v_cndmask_b32_e64 v99, v99, v255, s[6:7]
	v_pk_mul_f32 v[232:233], v[170:171], v[228:229]
	v_cndmask_b32_e32 v237, 1.0, v93, vcc
	v_cndmask_b32_e32 v238, 0, v97, vcc
	v_cndmask_b32_e64 v97, v87, v243, s[16:17]
	v_cndmask_b32_e64 v243, v87, v244, s[20:21]
	v_cndmask_b32_e64 v93, v87, v245, s[26:27]
	s_waitcnt lgkmcnt(0)
; __device__ __forceinline__ float fast_exp2(float x) { return __builtin_amdgcn_exp2f(x); }
; __device__ __forceinline__ float fast_rcp(float x) { return __builtin_amdgcn_rcpf(x); }
; template <int NB, bool MASK> __device__ __forceinline__ void sb_transform(f32x16* P, float& R, int hi, int kpos0, int qpos) {
;     float T[NB][4];
; #pragma unroll
;     for (int b = 0; b < NB; ++b)
; #pragma unroll
;         for (int g = 0; g < 4; ++g) {
;             float be[4], f[4];
; #pragma unroll
;             for (int i = 0; i < 4; ++i) {
;                 const float z = fmaxf(P[b][4 * g + i], -100.f);
;                 const float e = fast_exp2(-z), rc = fast_rcp(1.f + e);
;                 be[i] = rc; f[i] = e * rc;
;                 if (MASK) { const bool ok = (kpos0 + 32 * b + 8 * g + 4 * hi + i) < qpos; be[i] = ok ? be[i] : 0.f; f[i] = ok ? f[i] : 1.f; }
;             }
;             const float e2 = f[3], e1 = f[2] * f[3], e0 = f[1] * e1;
;             T[b][g] = f[0] * e0;
;             P[b][4 * g + 0] = be[0] * e0; P[b][4 * g + 1] = be[1] * e1; P[b][4 * g + 2] = be[2] * e2; P[b][4 * g + 3] = be[3];
;         }
;     float E = R;
; #pragma unroll
;     for (int b = NB - 1; b >= 0; --b)
; #pragma unroll
;         for (int g = 3; g >= 0; --g) {
;             const float To = __shfl_xor(T[b][g], 32);
;             const float Eg = hi ? E : E * To;
; #pragma unroll
;             for (int i = 0; i < 4; ++i) P[b][4 * g + i] *= Eg;
;             E = E * T[b][g] * To;
;         }
;     R = E;
; }
	v_pk_mul_f32 v[244:245], v[98:99], v[232:233]
	v_mov_b32_e32 v89, v244
	v_mov_b32_e32 v255, v244
	s_nop 1
	v_permlane32_swap_b32_e32 v89, v255
	v_cndmask_b32_e64 v89, v89, v255, s[6:7]
	v_cndmask_b32_e64 v239, v87, v95, s[8:9]
	v_mul_f32_e32 v242, v230, v90
	v_mov_b32_e32 v90, s45
	v_cndmask_b32_e64 v247, v87, v250, s[18:19]
	v_mul_f32_e32 v87, v171, v99
	v_mul_f32_e32 v229, v248, v249
	v_cndmask_b32_e64 v90, v90, v246, s[22:23]
	v_cndmask_b32_e64 v98, v171, v87, s[6:7]
	s_waitcnt lgkmcnt(0)
	v_mul_f32_e32 v87, v245, v89
	v_mul_f32_e32 v95, v173, v229
	v_mul_f32_e32 v246, v252, v90
	v_cndmask_b32_e64 v170, v245, v87, s[6:7]
	v_mul_f32_e32 v87, v244, v245
	v_mov_b32_e32 v90, v231
	v_pk_mul_f32 v[230:231], v[236:237], v[94:95]
	v_mul_f32_e32 v89, v87, v89
	v_mov_b32_e32 v87, v231
	v_mov_b32_e32 v255, v231
	s_nop 1
	v_permlane32_swap_b32_e32 v87, v255
	v_cndmask_b32_e64 v87, v87, v255, s[6:7]
	v_mov_b32_e32 v233, v228
	v_pk_mul_f32 v[96:97], v[232:233], v[96:97]
	v_pk_mul_f32 v[232:233], v[88:89], v[230:231]
	v_mov_b32_e32 v228, v95
	v_pk_mul_f32 v[90:91], v[90:91], v[92:93]
	v_pk_mul_f32 v[94:95], v[228:229], v[238:239]
	s_waitcnt lgkmcnt(0)
	v_pk_mul_f32 v[228:229], v[86:87], v[232:233]
	v_pk_mul_f32 v[90:91], v[90:91], v[98:99] op_sel_hi:[1,0]
	v_pk_mul_f32 v[92:93], v[246:247], v[98:99] op_sel_hi:[1,0]
	v_pk_mul_f32 v[96:97], v[96:97], v[170:171] op_sel_hi:[1,0]
	v_pk_mul_f32 v[98:99], v[242:243], v[170:171] op_sel_hi:[1,0]
	v_mov_b32_e32 v170, v228
	v_mov_b32_e32 v255, v228
	s_nop 1
	v_permlane32_swap_b32_e32 v170, v255
	v_cndmask_b32_e64 v170, v170, v255, s[6:7]
	v_mul_f32_e32 v86, v89, v87
	v_cndmask_b32_e64 v86, v89, v86, s[6:7]
	v_pk_mul_f32 v[88:89], v[94:95], v[86:87] op_sel_hi:[1,0]
	v_mov_b32_e32 v233, v230
	s_waitcnt lgkmcnt(0)
	v_mul_f32_e32 v94, v229, v170
	v_cndmask_b32_e64 v94, v229, v94, s[6:7]
	v_pk_mul_f32 v[84:85], v[232:233], v[84:85]
	v_mul_f32_e32 v173, v228, v229
	v_pk_mul_f32 v[86:87], v[240:241], v[86:87] op_sel_hi:[1,0]
	v_pk_mul_f32 v[84:85], v[84:85], v[94:95] op_sel_hi:[1,0]
	v_pk_mul_f32 v[94:95], v[234:235], v[94:95] op_sel_hi:[1,0]
	v_mul_f32_e32 v173, v173, v170
	s_mov_b64 s[8:9], 0
.LBB0_874:
	s_andn2_b64 vcc, exec, s[8:9]
	s_cbranch_vccnz .LBB0_876
	v_exp_f32_e32 v85, v227
	v_exp_f32_e32 v84, v226
	v_add_f32_e32 v87, 1.0, v85
	v_rcp_f32_e32 v94, v87
	v_exp_f32_e32 v86, v225
	v_add_f32_e32 v89, 1.0, v84
	v_exp_f32_e32 v224, v224
	v_rcp_f32_e32 v170, v89
	v_exp_f32_e32 v87, v223
	v_exp_f32_e32 v89, v222
	v_mul_f32_e32 v88, v85, v94
	v_add_f32_e32 v85, 1.0, v86
	v_exp_f32_e32 v90, v221
	v_rcp_f32_e32 v226, v85
	v_add_f32_e32 v85, 1.0, v224
	v_exp_f32_e32 v91, v189
	v_rcp_f32_e32 v222, v85
	v_add_f32_e32 v85, 1.0, v87
	v_rcp_f32_e32 v227, v85
	v_add_f32_e32 v85, 1.0, v89
	v_rcp_f32_e32 v189, v85
	v_add_f32_e32 v85, 1.0, v90
	v_rcp_f32_e32 v228, v85
	v_add_f32_e32 v85, 1.0, v91
	v_rcp_f32_e32 v229, v85
	v_exp_f32_e32 v85, v188
	v_mul_f32_e32 v225, v89, v189
	v_pk_mul_f32 v[90:91], v[90:91], v[228:229]
	v_pk_mul_f32 v[86:87], v[86:87], v[226:227]
	v_pk_mul_f32 v[230:231], v[90:91], v[90:91] op_sel:[0,1] op_sel_hi:[1,0]
	v_mul_f32_e32 v228, v228, v91
	v_exp_f32_e32 v90, v186
	v_exp_f32_e32 v91, v185
	v_add_f32_e32 v89, 1.0, v85
	v_rcp_f32_e32 v96, v89
	v_exp_f32_e32 v92, v187
	v_add_f32_e32 v89, 1.0, v90
	v_rcp_f32_e32 v98, v89
	v_add_f32_e32 v89, 1.0, v91
	v_rcp_f32_e32 v99, v89
	v_mul_f32_e32 v186, v85, v96
	v_add_f32_e32 v85, 1.0, v92
	v_rcp_f32_e32 v232, v85
	v_pk_mul_f32 v[90:91], v[90:91], v[98:99]
	v_mov_b32_e32 v85, v184
	v_pk_mul_f32 v[184:185], v[90:91], v[90:91] op_sel:[0,1] op_sel_hi:[1,0]
	v_exp_f32_e32 v182, v182
	v_mov_b32_e32 v89, v183
	v_exp_f32_e32 v183, v181
	v_exp_f32_e32 v85, v85
	v_exp_f32_e32 v234, v89
	v_add_f32_e32 v90, 1.0, v182
	v_rcp_f32_e32 v236, v90
	v_add_f32_e32 v90, 1.0, v183
	v_rcp_f32_e32 v237, v90
	v_add_f32_e32 v89, 1.0, v85
	v_rcp_f32_e32 v89, v89
	v_add_f32_e32 v90, 1.0, v234
	v_rcp_f32_e32 v238, v90
	v_pk_mul_f32 v[182:183], v[182:183], v[236:237]
	v_mul_f32_e32 v235, v85, v89
	v_pk_mul_f32 v[240:241], v[182:183], v[182:183] op_sel:[0,1] op_sel_hi:[1,0]
	v_xor_b32_e32 v85, 32, v191
	v_mov_b32_e32 v239, v240
	v_add_u32_e32 v90, 64, v192
	v_pk_mul_f32 v[234:235], v[234:235], v[238:239]
	v_cmp_lt_i32_e32 vcc, v85, v90
	v_mov_b32_e32 v93, v234
	v_mov_b32_e32 v233, v235
	v_cndmask_b32_e32 v85, v191, v85, vcc
	v_lshlrev_b32_e32 v95, 2, v85
	v_pk_mul_f32 v[92:93], v[92:93], v[232:233]
	v_mov_b32_e32 v187, v93
	v_mov_b32_e32 v255, v93
	s_nop 1
	v_permlane32_swap_b32_e32 v187, v255
	v_cndmask_b32_e64 v187, v187, v255, s[6:7]
	v_mov_b32_e32 v185, v171
	v_mul_f32_e32 v236, v236, v183
	v_pk_mul_f32 v[182:183], v[184:185], v[92:93]
	v_mov_b32_e32 v223, v230
	s_waitcnt lgkmcnt(0)
	v_mul_f32_e32 v85, v171, v187
	v_pk_mul_f32 v[186:187], v[182:183], v[186:187]
	v_cndmask_b32_e64 v92, v171, v85, s[6:7]
	v_mov_b32_e32 v171, v186
	v_mov_b32_e32 v255, v186
	s_nop 1
	v_permlane32_swap_b32_e32 v171, v255
	v_cndmask_b32_e64 v171, v171, v255, s[6:7]
	v_mov_b32_e32 v97, v232
	v_mov_b32_e32 v183, v184
	v_pk_mul_f32 v[184:185], v[224:225], v[222:223]
	v_pk_mul_f32 v[96:97], v[96:97], v[182:183]
	s_waitcnt lgkmcnt(0)
	v_mul_f32_e32 v85, v187, v171
	v_cndmask_b32_e64 v188, v187, v85, s[6:7]
	v_pk_mul_f32 v[182:183], v[186:187], v[186:187] op_sel_hi:[0,1]
	v_pk_mul_f32 v[186:187], v[86:87], v[184:185]
	v_mov_b32_e32 v239, v89
	v_mov_b32_e32 v89, v187
	v_mov_b32_e32 v255, v187
	s_nop 1
	v_permlane32_swap_b32_e32 v89, v255
	v_cndmask_b32_e64 v89, v89, v255, s[6:7]
	v_mov_b32_e32 v85, v183
	v_pk_mul_f32 v[84:85], v[84:85], v[170:171]
	v_mul_f32_e32 v98, v98, v91
	v_pk_mul_f32 v[182:183], v[186:187], v[84:85]
	v_pk_mul_f32 v[96:97], v[96:97], v[188:189] op_sel_hi:[1,0]
	v_pk_mul_f32 v[98:99], v[98:99], v[188:189] op_sel_hi:[1,0]
	v_mul_f32_e32 v224, v226, v184
	v_mov_b32_e32 v188, v227
	s_waitcnt lgkmcnt(0)
	v_pk_mul_f32 v[226:227], v[182:183], v[88:89]
	v_mov_b32_e32 v171, v226
	v_mov_b32_e32 v255, v226
	s_nop 1
	v_permlane32_swap_b32_e32 v171, v255
	v_cndmask_b32_e64 v171, v171, v255, s[6:7]
	v_mul_f32_e32 v84, v85, v89
	v_pk_mov_b32 v[86:87], v[184:185], v[230:231] op_sel:[1,0]
	v_cndmask_b32_e64 v84, v85, v84, s[6:7]
	v_pk_mul_f32 v[86:87], v[188:189], v[86:87]
	v_pk_mov_b32 v[90:91], v[234:235], v[240:241] op_sel:[1,0]
	v_pk_mul_f32 v[88:89], v[86:87], v[84:85] op_sel_hi:[1,0]
	v_pk_mul_f32 v[86:87], v[228:229], v[84:85] op_sel_hi:[1,0]
	s_waitcnt lgkmcnt(0)
	v_mul_f32_e32 v84, v227, v171
	v_mov_b32_e32 v95, v170
	v_mov_b32_e32 v183, v186
	v_pk_mul_f32 v[90:91], v[238:239], v[90:91]
	v_cndmask_b32_e64 v184, v227, v84, s[6:7]
	v_pk_mul_f32 v[84:85], v[94:95], v[182:183]
	v_mov_b32_e32 v225, v222
	v_mul_f32_e32 v170, v226, v227
	v_pk_mul_f32 v[90:91], v[90:91], v[92:93] op_sel_hi:[1,0]
	v_pk_mul_f32 v[92:93], v[236:237], v[92:93] op_sel_hi:[1,0]
	v_pk_mul_f32 v[84:85], v[84:85], v[184:185] op_sel_hi:[1,0]
	v_pk_mul_f32 v[94:95], v[224:225], v[184:185] op_sel_hi:[1,0]
	v_mul_f32_e32 v173, v170, v171
; #define SBAR() __builtin_amdgcn_sched_barrier(0)
; template <int D0, int KS0> __device__ __forceinline__ void pv_one(f32x16& od, int vb, const bf16x8* pa) {
;     const s16x4 l0 = tr_read<v_rd_off(D0, KS0, 0)>(vb), h0 = tr_read<v_rd_off(D0, KS0, 1)>(vb), l1 = tr_read<v_rd_off(D0, KS0 + 1, 0)>(vb), h1 = tr_read<v_rd_off(D0, KS0 + 1, 1)>(vb);
;     asm volatile("s_waitcnt lgkmcnt(0)" ::: "memory"); SBAR();
;     od = __builtin_amdgcn_mfma_f32_32x32x16_bf16(pa[0], PKV(l0, h0), od, 0, 0, 0);
;     od = __builtin_amdgcn_mfma_f32_32x32x16_bf16(pa[1], PKV(l1, h1), od, 0, 0, 0);
; }
; template <int KS0> __device__ __forceinline__ void pv_blk(f32x16* o, int vb, const bf16x8* pa) {
;     pv_one<0, KS0>(o[0], vb, pa); pv_one<1, KS0>(o[1], vb, pa); pv_one<2, KS0>(o[2], vb, pa); pv_one<3, KS0>(o[3], vb, pa);
; }
; __device__ __forceinline__ void pack_p(const f32x16& P, bf16x8& out0, bf16x8& out1) {
;     ...
;     PK4(0, out0); PK4(8, out1);
;     ...
; }
; template <int MODE> ...
;     ...
;             ATT_BLOCK(1);
;             ATT_BLOCK(0);
.LBB0_876:
	v_cvt_pk_bf16_f32 v182, v84, v85
	v_cvt_pk_bf16_f32 v183, v94, v95
	v_cvt_pk_bf16_f32 v184, v88, v89
	v_cvt_pk_bf16_f32 v185, v86, v87
	v_cvt_pk_bf16_f32 v234, v96, v97
	v_cvt_pk_bf16_f32 v235, v98, v99
	v_cvt_pk_bf16_f32 v236, v90, v91
	v_cvt_pk_bf16_f32 v237, v92, v93
	s_nop 0
	v_permlane32_swap_b32_e32 v182, v184
	v_permlane32_swap_b32_e32 v183, v185
	v_permlane32_swap_b32_e32 v234, v236
	v_permlane32_swap_b32_e32 v235, v237
	v_add_u32_e32 v170, s87, v220
	ds_read_b64_tr_b16 v[84:85], v170 offset:0x2000
	ds_read_b64_tr_b16 v[86:87], v170 offset:0x2800
	ds_read_b64_tr_b16 v[88:89], v170 offset:0x3000
	ds_read_b64_tr_b16 v[90:91], v170 offset:0x3800
	s_waitcnt lgkmcnt(0)
	s_nop 0
	v_mfma_f32_32x32x16_bf16 v[52:67], v[182:185], v[84:87], v[52:67]
	ds_read_b64_tr_b16 v[84:85], v170 offset:0x2200
	ds_read_b64_tr_b16 v[86:87], v170 offset:0x2a00
	ds_read_b64_tr_b16 v[92:93], v170 offset:0x3200
	ds_read_b64_tr_b16 v[94:95], v170 offset:0x3a00
	s_waitcnt lgkmcnt(0)
	v_mfma_f32_32x32x16_bf16 v[52:67], v[234:237], v[88:91], v[52:67]
	v_mfma_f32_32x32x16_bf16 v[36:51], v[182:185], v[84:87], v[36:51]
	ds_read_b64_tr_b16 v[84:85], v170 offset:0x2400
	ds_read_b64_tr_b16 v[86:87], v170 offset:0x2c00
	ds_read_b64_tr_b16 v[88:89], v170 offset:0x3400
	ds_read_b64_tr_b16 v[90:91], v170 offset:0x3c00
	s_waitcnt lgkmcnt(0)
	v_mfma_f32_32x32x16_bf16 v[36:51], v[234:237], v[92:95], v[36:51]
	v_mfma_f32_32x32x16_bf16 v[20:35], v[182:185], v[84:87], v[20:35]
	ds_read_b64_tr_b16 v[84:85], v170 offset:0x2600
	ds_read_b64_tr_b16 v[86:87], v170 offset:0x2e00
	ds_read_b64_tr_b16 v[238:239], v170 offset:0x3600
	ds_read_b64_tr_b16 v[240:241], v170 offset:0x3e00
	s_waitcnt lgkmcnt(0)
	v_mfma_f32_32x32x16_bf16 v[20:35], v[234:237], v[88:91], v[20:35]
	v_mfma_f32_32x32x16_bf16 v[4:19], v[182:185], v[84:87], v[4:19]
	ds_read_b128 v[182:185], v172 offset:32768
	ds_read_b128 v[186:189], v174 offset:32768
	s_mov_b64 s[8:9], -1
	s_andn2_b64 vcc, exec, s[50:51]
	s_waitcnt lgkmcnt(1)
	v_mfma_f32_32x32x16_bf16 v[84:99], v[182:185], v[100:103], v[68:83]
	s_waitcnt lgkmcnt(0)
	v_mfma_f32_32x32x16_bf16 v[84:99], v[186:189], v[104:107], v[84:99]
	ds_read_b128 v[182:185], v175 offset:32768
	ds_read_b128 v[186:189], v176 offset:32768
	s_waitcnt lgkmcnt(1)
	v_mfma_f32_32x32x16_bf16 v[84:99], v[182:185], v[108:111], v[84:99]
	ds_read_b128 v[174:177], v177 offset:32768
	ds_read_b128 v[182:185], v178 offset:32768
	s_waitcnt lgkmcnt(2)
	v_mfma_f32_32x32x16_bf16 v[84:99], v[186:189], v[112:115], v[84:99]
	s_waitcnt lgkmcnt(1)
	v_mfma_f32_32x32x16_bf16 v[84:99], v[174:177], v[116:119], v[84:99]
	ds_read_b128 v[174:177], v179 offset:32768
	ds_read_b128 v[222:225], v180 offset:32768
	s_waitcnt lgkmcnt(2)
	v_mfma_f32_32x32x16_bf16 v[84:99], v[182:185], v[120:123], v[84:99]
	s_waitcnt lgkmcnt(1)
	v_mfma_f32_32x32x16_bf16 v[84:99], v[174:177], v[124:127], v[84:99]
	s_waitcnt lgkmcnt(0)
	v_mfma_f32_32x32x16_bf16 v[84:99], v[222:225], v[128:131], v[84:99]
	v_mfma_f32_32x32x16_bf16 v[4:19], v[234:237], v[238:241], v[4:19]
	s_nop 10
	v_min_f32_e64 v232, -v84, s99
	v_min_f32_e64 v231, -v85, s99
	v_min_f32_e64 v230, -v86, s99
	v_min_f32_e64 v229, -v87, s99
	v_min_f32_e64 v228, -v88, s99
	v_min_f32_e64 v227, -v89, s99
	v_min_f32_e64 v226, -v90, s99
	v_min_f32_e64 v225, -v91, s99
	v_min_f32_e64 v224, -v92, s99
	v_min_f32_e64 v223, -v93, s99
	v_min_f32_e64 v222, -v94, s99
	v_min_f32_e64 v221, -v95, s99
	v_min_f32_e64 v94, -v96, s99
	v_min_f32_e64 v95, -v97, s99
	v_min_f32_e64 v93, -v98, s99
	v_min_f32_e64 v92, -v99, s99
	s_cbranch_vccnz .LBB0_878
	v_exp_f32_e32 v84, v232
	v_exp_f32_e32 v85, v231
	v_add_f32_e32 v86, 1.0, v84
	v_rcp_f32_e32 v86, v86
	v_add_f32_e32 v87, 1.0, v85
	v_exp_f32_e32 v97, v228
	v_rcp_f32_e32 v87, v87
	v_exp_f32_e32 v91, v227
	v_exp_f32_e32 v90, v229
	v_mul_f32_e32 v88, v84, v86
	v_cmp_lt_i32_e32 vcc, v2, v168
	v_or_b32_e32 v89, 1, v2
	v_add_f32_e32 v99, 1.0, v91
	v_cndmask_b32_e32 v84, 0, v86, vcc
	v_cndmask_b32_e32 v86, 1.0, v88, vcc
	v_mul_f32_e32 v88, v85, v87
	v_mov_b32_e32 v85, s45
	v_cmp_lt_i32_e32 vcc, v89, v168
	v_rcp_f32_e32 v171, v99
	v_cndmask_b32_e32 v85, v85, v87, vcc
	v_exp_f32_e32 v96, v230
	v_add_f32_e32 v87, 1.0, v90
	v_exp_f32_e32 v172, v226
	v_rcp_f32_e32 v89, v87
	v_add_f32_e32 v87, 1.0, v96
	v_rcp_f32_e32 v98, v87
	v_add_f32_e32 v174, 1.0, v172
	v_mul_f32_e32 v87, v90, v89
	v_or_b32_e32 v90, 3, v2
	v_rcp_f32_e32 v175, v174
	v_cndmask_b32_e32 v88, 1.0, v88, vcc
	v_cmp_lt_i32_e32 vcc, v90, v168
	v_exp_f32_e32 v174, v225
	v_cndmask_b32_e32 v90, 1.0, v87, vcc
	v_add_f32_e32 v87, 1.0, v97
	v_rcp_f32_e32 v99, v87
	v_mul_f32_e32 v87, v91, v171
	v_or_b32_e32 v91, 9, v2
	v_cmp_lt_i32_e64 s[8:9], v91, v168
	v_exp_f32_e32 v182, v95
	v_or_b32_e32 v179, 19, v2
	v_cndmask_b32_e64 v91, 1.0, v87, s[8:9]
	v_mul_f32_e32 v87, v172, v175
	v_add_f32_e32 v172, 1.0, v174
	v_rcp_f32_e32 v181, v172
	v_or_b32_e32 v172, 10, v2
	v_cmp_lt_i32_e64 s[10:11], v172, v168
	v_or_b32_e32 v172, 11, v2
	v_cmp_lt_i32_e64 s[12:13], v172, v168
	v_cndmask_b32_e64 v233, 1.0, v87, s[10:11]
	v_mul_f32_e32 v87, v174, v181
	v_exp_f32_e32 v174, v224
	v_cndmask_b32_e64 v242, 1.0, v87, s[12:13]
	v_exp_f32_e32 v87, v223
	v_add_f32_e32 v172, 1.0, v174
	v_rcp_f32_e32 v184, v172
	v_or_b32_e32 v172, 16, v2
	v_cmp_lt_i32_e64 s[14:15], v172, v168
	v_exp_f32_e32 v177, v221
	v_add_f32_e32 v176, 1.0, v87
	v_rcp_f32_e32 v185, v176
	v_exp_f32_e32 v176, v222
	v_add_f32_e32 v178, 1.0, v177
	v_cmp_lt_i32_e64 s[20:21], v179, v168
	v_add_f32_e32 v179, 1.0, v182
	v_rcp_f32_e32 v186, v178
	v_rcp_f32_e32 v234, v179
	v_or_b32_e32 v172, 17, v2
	v_exp_f32_e32 v183, v93
	v_mul_f32_e32 v87, v87, v185
; __device__ __forceinline__ float fast_exp2(float x) { return __builtin_amdgcn_exp2f(x); }
; __device__ __forceinline__ float fast_rcp(float x) { return __builtin_amdgcn_rcpf(x); }
; template <int NB, bool MASK> __device__ __forceinline__ void sb_transform(f32x16* P, float& R, int hi, int kpos0, int qpos) {
;     float T[NB][4];
; #pragma unroll
;     for (int b = 0; b < NB; ++b)
; #pragma unroll
;         for (int g = 0; g < 4; ++g) {
;             float be[4], f[4];
; #pragma unroll
;             for (int i = 0; i < 4; ++i) {
;                 const float z = fmaxf(P[b][4 * g + i], -100.f);
;                 const float e = fast_exp2(-z), rc = fast_rcp(1.f + e);
;                 be[i] = rc; f[i] = e * rc;
;                 if (MASK) { const bool ok = (kpos0 + 32 * b + 8 * g + 4 * hi + i) < qpos; be[i] = ok ? be[i] : 0.f; f[i] = ok ? f[i] : 1.f; }
;             }
;             const float e2 = f[3], e1 = f[2] * f[3], e0 = f[1] * e1;
;             T[b][g] = f[0] * e0;
;             P[b][4 * g + 0] = be[0] * e0; P[b][4 * g + 1] = be[1] * e1; P[b][4 * g + 2] = be[2] * e2; P[b][4 * g + 3] = be[3];
;         }
;     float E = R;
; #pragma unroll
;     for (int b = NB - 1; b >= 0; --b)
; #pragma unroll
;         for (int g = 3; g >= 0; --g) {
;             const float To = __shfl_xor(T[b][g], 32);
;             const float Eg = hi ? E : E * To;
; #pragma unroll
;             for (int i = 0; i < 4; ++i) P[b][4 * g + i] *= Eg;
;             E = E * T[b][g] * To;
;         }
;     R = E;
; }
	v_cmp_lt_i32_e64 s[16:17], v172, v168
	v_mul_f32_e32 v174, v174, v184
	v_add_f32_e32 v187, 1.0, v183
	v_cndmask_b32_e64 v172, 1.0, v87, s[16:17]
	v_add_f32_e32 v87, 1.0, v176
	v_rcp_f32_e32 v178, v87
	v_mul_f32_e32 v87, v177, v186
	v_exp_f32_e32 v177, v94
	v_rcp_f32_e32 v238, v187
	v_exp_f32_e32 v187, v92
	v_cndmask_b32_e64 v180, 1.0, v87, s[20:21]
	v_add_f32_e32 v87, 1.0, v177
	v_rcp_f32_e32 v179, v87
	v_mul_f32_e32 v87, v182, v234
	v_or_b32_e32 v182, 25, v2
	v_cmp_lt_i32_e64 s[26:27], v182, v168
	v_add_f32_e32 v182, 1.0, v187
	v_rcp_f32_e32 v240, v182
	v_or_b32_e32 v182, 26, v2
	v_cndmask_b32_e64 v236, 1.0, v87, s[26:27]
	v_mul_f32_e32 v87, v183, v238
	v_cmp_lt_i32_e64 s[22:23], v182, v168
	v_or_b32_e32 v182, 27, v2
	v_cmp_lt_i32_e64 s[18:19], v182, v168
	v_cndmask_b32_e64 v235, 1.0, v87, s[22:23]
	v_mul_f32_e32 v87, v187, v240
	v_cndmask_b32_e64 v243, 1.0, v87, s[18:19]
	v_xor_b32_e32 v87, 32, v191
	v_add_u32_e32 v182, 64, v192
	v_cmp_lt_i32_e64 s[28:29], v87, v182
	v_or_b32_e32 v182, 18, v2
	v_cmp_lt_i32_e64 s[30:31], v182, v168
	v_cndmask_b32_e64 v87, v191, v87, s[28:29]
	v_lshlrev_b32_e32 v244, 2, v87
	v_or_b32_e32 v87, 24, v2
	v_or_b32_e32 v182, 8, v2
	v_or_b32_e32 v2, 2, v2
	v_pk_mul_f32 v[176:177], v[176:177], v[178:179]
	v_cmp_lt_i32_e64 s[28:29], v87, v1
	v_cmp_lt_i32_e64 s[34:35], v2, v168
	v_mov_b32_e32 v87, s45
	v_mul_f32_e32 v235, v235, v243
	v_cndmask_b32_e64 v177, 1.0, v177, s[28:29]
	v_cndmask_b32_e64 v176, 1.0, v176, s[30:31]
	v_cndmask_b32_e64 v2, 0, v98, s[34:35]
	v_cndmask_b32_e64 v183, v87, v181, s[12:13]
	v_mul_f32_e32 v181, v236, v235
	v_mul_f32_e32 v188, v90, v2
	v_mov_b32_e32 v2, s45
	v_pk_mul_f32 v[236:237], v[176:177], v[180:181]
	v_cndmask_b32_e64 v2, v2, v175, s[10:11]
	v_mov_b32_e32 v175, v237
	v_mov_b32_e32 v255, v237
	s_nop 1
	v_permlane32_swap_b32_e32 v175, v255
	v_cndmask_b32_e64 v175, v175, v255, s[6:7]
	v_cndmask_b32_e32 v189, v87, v89, vcc
	v_cmp_lt_i32_e32 vcc, v182, v1
	v_mul_f32_e32 v182, v242, v2
	v_mov_b32_e32 v2, s45
	v_cndmask_b32_e64 v184, v2, v184, s[14:15]
	v_cndmask_b32_e64 v2, 0, v178, s[30:31]
	v_cndmask_b32_e64 v187, v87, v186, s[20:21]
	v_mul_f32_e32 v186, v180, v2
	v_mov_b32_e32 v2, s45
	v_cndmask_b32_e64 v174, 1.0, v174, s[14:15]
	v_cndmask_b32_e64 v2, v2, v238, s[22:23]
	v_pk_mul_f32 v[238:239], v[172:173], v[236:237]
	v_cndmask_b32_e64 v185, v87, v185, s[16:17]
	s_waitcnt lgkmcnt(0)
	v_pk_mul_f32 v[176:177], v[174:175], v[238:239]
	v_mov_b32_e32 v89, v176
	v_mov_b32_e32 v255, v176
	s_nop 1
	v_permlane32_swap_b32_e32 v89, v255
	v_cndmask_b32_e64 v89, v89, v255, s[6:7]
	v_cndmask_b32_e64 v178, 0, v179, s[28:29]
	v_cndmask_b32_e64 v179, v87, v234, s[26:27]
	v_mov_b32_e32 v234, v181
	v_mov_b32_e32 v239, v236
	v_pk_mul_f32 v[96:97], v[96:97], v[98:99]
	v_cndmask_b32_e64 v241, v87, v240, s[18:19]
	v_mul_f32_e32 v240, v243, v2
	v_mul_f32_e32 v2, v173, v175
	v_pk_mul_f32 v[174:175], v[234:235], v[178:179]
	v_pk_mul_f32 v[178:179], v[238:239], v[184:185]
	v_mul_f32_e32 v185, v233, v242
	v_cndmask_b32_e32 v97, 1.0, v97, vcc
	v_cndmask_b32_e64 v96, 1.0, v96, s[34:35]
	v_cndmask_b32_e32 v98, 0, v99, vcc
	v_cndmask_b32_e64 v99, v87, v171, s[8:9]
	s_waitcnt lgkmcnt(0)
	v_mul_f32_e32 v87, v177, v89
	v_mul_f32_e32 v91, v91, v185
	v_cndmask_b32_e64 v172, v177, v87, s[6:7]
	v_mul_f32_e32 v87, v176, v177
	v_pk_mul_f32 v[96:97], v[96:97], v[90:91]
	v_mul_f32_e32 v89, v87, v89
	v_mov_b32_e32 v87, v97
	v_mov_b32_e32 v255, v97
	s_nop 1
	v_permlane32_swap_b32_e32 v87, v255
	v_cndmask_b32_e64 v87, v87, v255, s[6:7]
	v_pk_mul_f32 v[180:181], v[186:187], v[172:173] op_sel_hi:[1,0]
	v_pk_mul_f32 v[186:187], v[88:89], v[96:97]
	v_mov_b32_e32 v184, v91
	v_pk_mul_f32 v[90:91], v[184:185], v[98:99]
	s_waitcnt lgkmcnt(0)
	v_pk_mul_f32 v[98:99], v[86:87], v[186:187]
	v_mov_b32_e32 v86, v98
	v_mov_b32_e32 v255, v98
	s_nop 1
	v_permlane32_swap_b32_e32 v86, v255
	v_cndmask_b32_e64 v86, v86, v255, s[6:7]
	v_cndmask_b32_e64 v2, v173, v2, s[6:7]
	v_pk_mul_f32 v[176:177], v[174:175], v[2:3] op_sel_hi:[1,0]
	v_pk_mul_f32 v[174:175], v[240:241], v[2:3] op_sel_hi:[1,0]
	v_mul_f32_e32 v2, v89, v87
	v_cndmask_b32_e64 v2, v89, v2, s[6:7]
	v_pk_mul_f32 v[184:185], v[90:91], v[2:3] op_sel_hi:[1,0]
	v_pk_mul_f32 v[182:183], v[182:183], v[2:3] op_sel_hi:[1,0]
	s_waitcnt lgkmcnt(0)
	v_mul_f32_e32 v2, v99, v86
	v_mov_b32_e32 v187, v96
	v_cndmask_b32_e64 v2, v99, v2, s[6:7]
	v_pk_mul_f32 v[84:85], v[186:187], v[84:85]
	v_pk_mul_f32 v[188:189], v[188:189], v[2:3] op_sel_hi:[1,0]
	v_pk_mul_f32 v[186:187], v[84:85], v[2:3] op_sel_hi:[1,0]
	v_mul_f32_e32 v2, v98, v99
	v_pk_mul_f32 v[178:179], v[178:179], v[172:173] op_sel_hi:[1,0]
	v_mul_f32_e32 v171, v2, v86
	s_mov_b64 s[8:9], 0
; __device__ __forceinline__ float fast_exp2(float x) { return __builtin_amdgcn_exp2f(x); }
; __device__ __forceinline__ float fast_rcp(float x) { return __builtin_amdgcn_rcpf(x); }
; template <int NB, bool MASK> __device__ __forceinline__ void sb_transform(f32x16* P, float& R, int hi, int kpos0, int qpos) {
;     float T[NB][4];
; #pragma unroll
;     for (int b = 0; b < NB; ++b)
; #pragma unroll
;         for (int g = 0; g < 4; ++g) {
;             float be[4], f[4];
; #pragma unroll
;             for (int i = 0; i < 4; ++i) {
;                 const float z = fmaxf(P[b][4 * g + i], -100.f);
;                 const float e = fast_exp2(-z), rc = fast_rcp(1.f + e);
;                 be[i] = rc; f[i] = e * rc;
;                 if (MASK) { const bool ok = (kpos0 + 32 * b + 8 * g + 4 * hi + i) < qpos; be[i] = ok ? be[i] : 0.f; f[i] = ok ? f[i] : 1.f; }
;             }
;             const float e2 = f[3], e1 = f[2] * f[3], e0 = f[1] * e1;
;             T[b][g] = f[0] * e0;
;             P[b][4 * g + 0] = be[0] * e0; P[b][4 * g + 1] = be[1] * e1; P[b][4 * g + 2] = be[2] * e2; P[b][4 * g + 3] = be[3];
;         }
;     float E = R;
; #pragma unroll
;     for (int b = NB - 1; b >= 0; --b)
; #pragma unroll
;         for (int g = 3; g >= 0; --g) {
;             const float To = __shfl_xor(T[b][g], 32);
;             const float Eg = hi ? E : E * To;
; #pragma unroll
;             for (int i = 0; i < 4; ++i) P[b][4 * g + i] *= Eg;
;             E = E * T[b][g] * To;
;         }
;     R = E;
; }
.LBB0_878:
	s_andn2_b64 vcc, exec, s[8:9]
	s_cbranch_vccnz .LBB0_880
	v_exp_f32_e32 v2, v232
	v_exp_f32_e32 v84, v231
	v_add_f32_e32 v86, 1.0, v2
	v_rcp_f32_e32 v86, v86
	v_exp_f32_e32 v88, v230
	v_add_f32_e32 v85, 1.0, v84
	v_exp_f32_e32 v96, v229
	v_rcp_f32_e32 v98, v85
	v_exp_f32_e32 v89, v228
	v_exp_f32_e32 v85, v227
	v_mul_f32_e32 v90, v2, v86
	v_add_f32_e32 v2, 1.0, v88
	v_exp_f32_e32 v174, v226
	v_rcp_f32_e32 v182, v2
	v_add_f32_e32 v2, 1.0, v96
	v_exp_f32_e32 v175, v225
	v_rcp_f32_e32 v172, v2
	v_add_f32_e32 v2, 1.0, v89
	v_rcp_f32_e32 v183, v2
	v_add_f32_e32 v2, 1.0, v85
	v_rcp_f32_e32 v185, v2
	v_add_f32_e32 v2, 1.0, v174
	v_rcp_f32_e32 v186, v2
	v_add_f32_e32 v2, 1.0, v175
	v_rcp_f32_e32 v187, v2
	v_exp_f32_e32 v2, v224
	v_mul_f32_e32 v97, v85, v185
	v_pk_mul_f32 v[174:175], v[174:175], v[186:187]
	v_add_f32_e32 v85, 1.0, v2
	v_rcp_f32_e32 v178, v85
	v_pk_mul_f32 v[188:189], v[174:175], v[174:175] op_sel:[0,1] op_sel_hi:[1,0]
	v_exp_f32_e32 v174, v222
	v_exp_f32_e32 v176, v223
	v_mul_f32_e32 v186, v186, v175
	v_exp_f32_e32 v175, v221
	v_exp_f32_e32 v228, v93
	v_add_f32_e32 v85, 1.0, v174
	v_mul_f32_e32 v222, v2, v178
	v_add_f32_e32 v2, 1.0, v176
	v_exp_f32_e32 v229, v92
	v_rcp_f32_e32 v180, v85
	v_add_f32_e32 v85, 1.0, v175
	v_rcp_f32_e32 v224, v2
	v_rcp_f32_e32 v181, v85
	v_exp_f32_e32 v2, v95
	v_exp_f32_e32 v94, v94
	v_add_f32_e32 v87, 1.0, v228
	v_rcp_f32_e32 v92, v87
	v_add_f32_e32 v87, 1.0, v229
	v_rcp_f32_e32 v93, v87
	v_add_f32_e32 v85, 1.0, v2
	v_rcp_f32_e32 v85, v85
	v_add_f32_e32 v87, 1.0, v94
	v_rcp_f32_e32 v230, v87
	v_pk_mul_f32 v[228:229], v[228:229], v[92:93]
	v_mul_f32_e32 v95, v2, v85
	v_pk_mul_f32 v[232:233], v[228:229], v[228:229] op_sel:[0,1] op_sel_hi:[1,0]
	v_xor_b32_e32 v2, 32, v191
	v_mov_b32_e32 v231, v232
	v_add_u32_e32 v87, 64, v192
	v_pk_mul_f32 v[94:95], v[94:95], v[230:231]
	v_cmp_lt_i32_e32 vcc, v2, v87
	v_mov_b32_e32 v177, v94
	v_mov_b32_e32 v225, v95
	v_cndmask_b32_e32 v2, v191, v2, vcc
	v_lshlrev_b32_e32 v87, 2, v2
	v_pk_mul_f32 v[176:177], v[176:177], v[224:225]
	v_mov_b32_e32 v223, v177
	v_mov_b32_e32 v255, v177
	s_nop 1
	v_permlane32_swap_b32_e32 v223, v255
	v_cndmask_b32_e64 v223, v223, v255, s[6:7]
	v_pk_mul_f32 v[174:175], v[174:175], v[180:181]
	v_mul_f32_e32 v92, v92, v229
	v_pk_mul_f32 v[226:227], v[174:175], v[174:175] op_sel:[0,1] op_sel_hi:[1,0]
	v_mov_b32_e32 v231, v85
	v_mov_b32_e32 v227, v173
	v_pk_mul_f32 v[228:229], v[226:227], v[176:177]
	s_waitcnt lgkmcnt(0)
	v_mul_f32_e32 v2, v173, v223
	v_pk_mul_f32 v[222:223], v[228:229], v[222:223]
	v_mov_b32_e32 v99, v222
	v_mov_b32_e32 v255, v222
	s_nop 1
	v_permlane32_swap_b32_e32 v99, v255
	v_cndmask_b32_e64 v99, v99, v255, s[6:7]
	v_pk_mov_b32 v[94:95], v[94:95], v[232:233] op_sel:[1,0]
	v_cndmask_b32_e64 v2, v173, v2, s[6:7]
	v_pk_mul_f32 v[94:95], v[230:231], v[94:95]
	v_mov_b32_e32 v173, v188
	v_pk_mul_f32 v[176:177], v[94:95], v[2:3] op_sel_hi:[1,0]
	v_pk_mul_f32 v[88:89], v[88:89], v[182:183]
	v_pk_mul_f32 v[94:95], v[96:97], v[172:173]
	v_mul_f32_e32 v180, v180, v175
	v_pk_mul_f32 v[174:175], v[92:93], v[2:3] op_sel_hi:[1,0]
	s_waitcnt lgkmcnt(0)
	v_mul_f32_e32 v2, v223, v99
	v_mov_b32_e32 v179, v224
	v_mov_b32_e32 v229, v226
	v_pk_mul_f32 v[88:89], v[88:89], v[94:95]
	v_cndmask_b32_e64 v2, v223, v2, s[6:7]
	v_pk_mul_f32 v[92:93], v[178:179], v[228:229]
	v_mov_b32_e32 v91, v89
	v_mov_b32_e32 v255, v89
	s_nop 1
	v_permlane32_swap_b32_e32 v91, v255
	v_cndmask_b32_e64 v91, v91, v255, s[6:7]
	v_pk_mul_f32 v[178:179], v[92:93], v[2:3] op_sel_hi:[1,0]
	v_pk_mul_f32 v[92:93], v[222:223], v[222:223] op_sel_hi:[0,1]
	v_mov_b32_e32 v85, v93
	v_pk_mul_f32 v[84:85], v[84:85], v[98:99]
	v_pk_mul_f32 v[180:181], v[180:181], v[2:3] op_sel_hi:[1,0]
	v_pk_mul_f32 v[92:93], v[88:89], v[84:85]
	s_waitcnt lgkmcnt(0)
	v_mul_f32_e32 v2, v85, v91
	v_pk_mul_f32 v[90:91], v[92:93], v[90:91]
	v_mov_b32_e32 v89, v90
	v_mov_b32_e32 v255, v90
	s_nop 1
	v_permlane32_swap_b32_e32 v89, v255
	v_cndmask_b32_e64 v89, v89, v255, s[6:7]
	v_mul_f32_e32 v84, v182, v94
	v_mov_b32_e32 v184, v183
	v_pk_mov_b32 v[94:95], v[94:95], v[188:189] op_sel:[1,0]
	v_cndmask_b32_e64 v2, v85, v2, s[6:7]
	v_pk_mul_f32 v[94:95], v[184:185], v[94:95]
	v_pk_mul_f32 v[182:183], v[186:187], v[2:3] op_sel_hi:[1,0]
	v_pk_mul_f32 v[184:185], v[94:95], v[2:3] op_sel_hi:[1,0]
	s_waitcnt lgkmcnt(0)
	v_mul_f32_e32 v2, v91, v89
	v_mov_b32_e32 v87, v98
	v_mov_b32_e32 v93, v88
	v_cndmask_b32_e64 v2, v91, v2, s[6:7]
	v_pk_mul_f32 v[86:87], v[86:87], v[92:93]
	v_mov_b32_e32 v85, v172
	v_pk_mul_f32 v[186:187], v[86:87], v[2:3] op_sel_hi:[1,0]
	v_pk_mul_f32 v[188:189], v[84:85], v[2:3] op_sel_hi:[1,0]
	v_mul_f32_e32 v2, v90, v91
	v_mul_f32_e32 v171, v2, v89
